# recurrence chunk loop: packed fp32 VALU feeding MFMA operands split into scalar pairs
# baseline (speedup 1.0000x reference)
; #define LAS __attribute__((address_space(3)))
; __device__ __forceinline__ f32x4 mfma16(bf16x8 a, bf16x8 b, f32x4 c) { return __builtin_amdgcn_mfma_f32_16x16x32_bf16(a, b, c, 0, 0, 0); }
; __device__ __forceinline__ void g2_phase(const PP P, int l, LAS unsigned char* lds) {
;     ...
;                 bf16x8 Sh[2], Sl[2]; split8(S[0], S[1], Sh[0], Sl[0]); split8(S[2], S[3], Sh[1], Sl[1]);
;                 f32x4 U[4];
; #pragma unroll
;                 for (int mi = 0; mi < 4; ++mi) { f32x4 acc = {0.f, 0.f, 0.f, 0.f};
; #pragma unroll
;                     for (int kk = 0; kk < 2; ++kk) { const bf16x8 a = ldA2s(buf, 16 * mi + fr, kk, fq); acc = mfma16(a, Sh[kk], acc); if (GDN_SPLIT) acc = mfma16(a, Sl[kk], acc); }
; #pragma unroll
;                     for (int j = 0; j < 4; ++j) { const int i = 16 * mi + fq * 4 + j; U[mi][j] = *(const LAS float*)(buf + G2_UV + i * 272 + dv * 4) - acc[j];
;                         zr[mi][j] = bf2f(*(const LAS bf16*)(buf + G2_Z + i * 144 + dv * 2)); } }
;                 bf16x8 Uh[2], Ul[2]; split8(U[0], U[1], Uh[0], Ul[0]); split8(U[2], U[3], Uh[1], Ul[1]);
; #pragma unroll
;                 for (int mi = 0; mi < 4; ++mi) { f32x4 acc = {0.f, 0.f, 0.f, 0.f};
; #pragma unroll
;                     for (int kk = 0; kk < 2; ++kk) { const bf16x8 a = ldA2s(buf + 3 * G2_MAT, 16 * mi + fr, kk, fq); acc = mfma16(a, Sh[kk], acc); if (GDN_SPLIT) acc = mfma16(a, Sl[kk], acc);
;                         const bf16x8 a2 = ldA2s(buf + G2_MAT, 16 * mi + fr, kk, fq); acc = mfma16(a2, Uh[kk], acc); if (GDN_SPLIT) acc = mfma16(a2, Ul[kk], acc); }
.LBB0_128:
	s_or_saveexec_b64 s[56:57], s[56:57]
	s_and_b32 s71, s70, 1
	s_xor_b64 exec, exec, s[56:57]
	s_cbranch_execz .LBB0_162
	s_mul_i32 s58, s71, 0xf810
	s_add_i32 s58, s58, 0
	v_add3_u32 v179, s58, v119, v129
	ds_read2_b64 v[16:19], v179 offset1:4
	ds_read2_b64 v[20:23], v179 offset0:8 offset1:12
	s_waitcnt vmcnt(1)
	v_cvt_pk_bf16_f32 v92, v0, v1
	v_cvt_pk_bf16_f32 v93, v2, v3
	v_cvt_pk_bf16_f32 v94, v4, v5
	v_cvt_pk_bf16_f32 v95, v6, v7
	v_cvt_pk_bf16_f32 v36, v8, v9
	v_cvt_pk_bf16_f32 v37, v10, v11
	v_cvt_pk_bf16_f32 v38, v12, v13
	s_waitcnt lgkmcnt(1)
	v_mfma_f32_16x16x32_bf16 v[16:19], v[16:19], v[92:95], 0
	v_cvt_pk_bf16_f32 v39, v14, v15
	v_add_u32_e32 v28, s58, v121
	v_add_u32_e32 v29, s58, v123
	s_waitcnt lgkmcnt(0)
	v_mfma_f32_16x16x32_bf16 v[16:19], v[20:23], v[36:39], v[16:19]
	v_add_u32_e32 v20, v28, v131
	v_add_u32_e32 v21, v29, v133
	v_add_u32_e32 v100, v28, v135
	ds_read_b32 v20, v20 offset:36864
	ds_read_u16 v24, v21 offset:54272
	v_add_u32_e32 v21, 0x9000, v100
	ds_read2_b32 v[22:23], v21 offset1:68
	v_add_u32_e32 v101, v29, v137
	v_add_u32_e32 v28, 0x800, v179
	v_add_u32_e32 v188, 0x7800, v179
	v_add_u32_e32 v189, 0x3000, v179
	s_waitcnt lgkmcnt(0)
	v_mov_b32_e32 v21, v22
	v_sub_f32_e32 v16, v20, v16
	v_sub_f32_e32 v17, v21, v17
	ds_read_u16 v154, v101 offset:54272
	ds_read_u16 v148, v101 offset:54416
	ds_read_b32 v21, v100 offset:37408
	v_mov_b32_e32 v20, v23
	ds_read_u16 v155, v101 offset:54560
	s_waitcnt lgkmcnt(1)
	v_sub_f32_e32 v18, v20, v18
	v_sub_f32_e32 v19, v21, v19
	ds_read2_b64 v[20:23], v28 offset0:32 offset1:36
	ds_read2_b64 v[28:31], v28 offset0:40 offset1:44
	s_waitcnt lgkmcnt(1)
	v_mfma_f32_16x16x32_bf16 v[20:23], v[20:23], v[92:95], 0
	s_waitcnt lgkmcnt(0)
	v_mfma_f32_16x16x32_bf16 v[20:23], v[28:31], v[36:39], v[20:23]
	v_add_u32_e32 v28, 0x9e00, v100
	ds_read2_b32 v[28:29], v28 offset0:124 offset1:192
	ds_read_u16 v156, v101 offset:56432
	ds_read_u16 v158, v101 offset:56576
	s_waitcnt lgkmcnt(2)
	s_nop 2
	v_sub_f32_e32 v96, v28, v20
	v_sub_f32_e32 v97, v29, v21
	v_add_u32_e32 v20, 0xa000, v100
	ds_read2_b32 v[20:21], v20 offset0:132 offset1:200
	ds_read_u16 v157, v101 offset:56720
	v_add_u32_e32 v28, 0x1000, v179
	ds_read_u16 v159, v101 offset:56864
	v_cvt_pk_bf16_f32 v102, v96, v97
	s_waitcnt lgkmcnt(2)
	v_sub_f32_e32 v98, v20, v22
	v_sub_f32_e32 v99, v21, v23
	ds_read2_b64 v[20:23], v28 offset0:64 offset1:68
	ds_read2_b64 v[28:31], v28 offset0:72 offset1:76
	s_waitcnt lgkmcnt(1)
	v_mfma_f32_16x16x32_bf16 v[20:23], v[20:23], v[92:95], 0
	v_cvt_pk_bf16_f32 v103, v98, v99
	s_waitcnt lgkmcnt(0)
	v_mfma_f32_16x16x32_bf16 v[20:23], v[28:31], v[36:39], v[20:23]
	v_add_u32_e32 v28, 0xb000, v100
	ds_read2_b32 v[28:29], v28 offset0:60 offset1:128
	ds_read_u16 v161, v101 offset:58736
	ds_read_u16 v163, v101 offset:58880
	s_waitcnt lgkmcnt(2)
	s_nop 2
	v_sub_f32_e32 v184, v28, v20
	v_sub_f32_e32 v185, v29, v21
	v_add_u32_e32 v20, 0xb200, v100
	ds_read2_b32 v[20:21], v20 offset0:68 offset1:136
	ds_read_u16 v162, v101 offset:59024
	v_add_u32_e32 v28, 0x1800, v179
	ds_read_u16 v178, v101 offset:59168
	v_cvt_pk_bf16_f32 v96, v184, v185
	s_waitcnt lgkmcnt(2)
	v_sub_f32_e32 v186, v20, v22
	v_sub_f32_e32 v187, v21, v23
	ds_read2_b64 v[20:23], v28 offset0:96 offset1:100
	ds_read2_b64 v[28:31], v28 offset0:104 offset1:108
	s_waitcnt lgkmcnt(1)
	v_mfma_f32_16x16x32_bf16 v[20:23], v[20:23], v[92:95], 0
	v_cvt_pk_bf16_f32 v97, v186, v187
	v_add_u32_e32 v184, 0x7000, v179
	v_add_u32_e32 v185, 0x2800, v179
	s_waitcnt lgkmcnt(0)
	v_mfma_f32_16x16x32_bf16 v[20:23], v[28:31], v[36:39], v[20:23]
	v_add_u32_e32 v28, 0xc000, v100
	ds_read2_b32 v[28:29], v28 offset0:124 offset1:192
	ds_read_u16 v180, v101 offset:61040
	ds_read_u16 v182, v101 offset:61184
	s_waitcnt lgkmcnt(2)
	s_nop 2
	v_sub_f32_e32 v20, v28, v20
	v_sub_f32_e32 v21, v29, v21
	v_add_u32_e32 v28, 0xc400, v100
	ds_read2_b32 v[28:29], v28 offset0:4 offset1:72
	ds_read_u16 v181, v101 offset:61328
	ds_read_u16 v183, v101 offset:61472
	v_cvt_pk_bf16_f32 v100, v16, v17
	v_cvt_pk_bf16_f32 v101, v18, v19
	s_waitcnt lgkmcnt(2)
	v_sub_f32_e32 v22, v28, v22
	v_sub_f32_e32 v23, v29, v23
	v_add_u32_e32 v28, 0x6800, v179
	ds_read2_b64 v[16:19], v28 offset0:128 offset1:132
	v_add_u32_e32 v29, 0x2000, v179
	v_cvt_pk_bf16_f32 v98, v20, v21
	v_cvt_pk_bf16_f32 v99, v22, v23
	ds_read2_b64 v[20:23], v29 offset0:128 offset1:132
	s_waitcnt lgkmcnt(1)
	v_mfma_f32_16x16x32_bf16 v[16:19], v[16:19], v[92:95], 0
	s_waitcnt lgkmcnt(0)
	v_mfma_f32_16x16x32_bf16 v[16:19], v[20:23], v[100:103], v[16:19]
	ds_read2_b64 v[20:23], v28 offset0:136 offset1:140
	s_waitcnt lgkmcnt(0)
	v_mfma_f32_16x16x32_bf16 v[16:19], v[20:23], v[36:39], v[16:19]
	ds_read2_b64 v[20:23], v29 offset0:136 offset1:140
	ds_read2_b64 v[28:31], v185 offset0:160 offset1:164
	s_waitcnt lgkmcnt(1)
	v_mfma_f32_16x16x32_bf16 v[16:19], v[20:23], v[96:99], v[16:19]
	ds_read2_b64 v[20:23], v184 offset0:160 offset1:164
	s_waitcnt lgkmcnt(0)
	v_mfma_f32_16x16x32_bf16 v[20:23], v[20:23], v[92:95], 0
	v_mfma_f32_16x16x32_bf16 v[20:23], v[28:31], v[100:103], v[20:23]
	ds_read2_b64 v[28:31], v184 offset0:168 offset1:172
	s_waitcnt lgkmcnt(0)
	v_mfma_f32_16x16x32_bf16 v[20:23], v[28:31], v[36:39], v[20:23]
	ds_read2_b64 v[28:31], v185 offset0:168 offset1:172
	ds_read2_b64 v[184:187], v189 offset0:192 offset1:196
	s_waitcnt lgkmcnt(1)
	v_mfma_f32_16x16x32_bf16 v[20:23], v[28:31], v[96:99], v[20:23]
	ds_read2_b64 v[28:31], v188 offset0:192 offset1:196
	s_waitcnt lgkmcnt(0)
	v_mfma_f32_16x16x32_bf16 v[28:31], v[28:31], v[92:95], 0
	v_mfma_f32_16x16x32_bf16 v[28:31], v[184:187], v[100:103], v[28:31]
	ds_read2_b64 v[184:187], v188 offset0:200 offset1:204
	v_add_u32_e32 v188, 0x8000, v179
	s_waitcnt lgkmcnt(0)
; #define LAS __attribute__((address_space(3)))
; __device__ __forceinline__ float row16_sum(float v) { v += dpp_f<0xB1>(v); v += dpp_f<0x4E>(v); v += dpp_f<0x141>(v); v += dpp_f<0x140>(v); return v; }
; __device__ __forceinline__ f32x4 mfma16(bf16x8 a, bf16x8 b, f32x4 c) { return __builtin_amdgcn_mfma_f32_16x16x32_bf16(a, b, c, 0, 0, 0); }
; __device__ __forceinline__ void g2_phase(const PP P, int l, LAS unsigned char* lds) {
;     ...
;                 for (int mi = 0; mi < 4; ++mi) { f32x4 acc = {0.f, 0.f, 0.f, 0.f};
; #pragma unroll
;                     for (int kk = 0; kk < 2; ++kk) { const bf16x8 a = ldA2s(buf + 3 * G2_MAT, 16 * mi + fr, kk, fq); acc = mfma16(a, Sh[kk], acc); if (GDN_SPLIT) acc = mfma16(a, Sl[kk], acc);
;                         const bf16x8 a2 = ldA2s(buf + G2_MAT, 16 * mi + fr, kk, fq); acc = mfma16(a2, Uh[kk], acc); if (GDN_SPLIT) acc = mfma16(a2, Ul[kk], acc); }
;                     O[mi] = acc; }
;                 const float gamL = *(const LAS float*)(buf + G2_GAM);
; #pragma unroll
;                 for (int m = 0; m < 4; ++m) { f32x4 acc = S[m] * gamL;
; #pragma unroll
;                     for (int kk = 0; kk < 2; ++kk) { const bf16x8 a = ldA2s(buf + 2 * G2_MAT, 16 * m + fr, kk, fq); acc = mfma16(a, Uh[kk], acc); if (GDN_SPLIT) acc = mfma16(a, Ul[kk], acc); }
;                     S[m] = acc; }
; #pragma unroll
;                 for (int mi = 0; mi < 4; ++mi)
; #pragma unroll
;                     for (int j = 0; j < 4; ++j) { const float s = row16_sum(O[mi][j] * O[mi][j]);
;                         if (fr == 0) red[(n & 1) * 256 + wave * 64 + 16 * mi + fq * 4 + j] = s; }
	v_mfma_f32_16x16x32_bf16 v[28:31], v[184:187], v[36:39], v[28:31]
	ds_read2_b64 v[184:187], v189 offset0:200 offset1:204
	v_add_u32_e32 v189, 0x3800, v179
	s_waitcnt lgkmcnt(0)
	v_mfma_f32_16x16x32_bf16 v[28:31], v[184:187], v[96:99], v[28:31]
	ds_read2_b64 v[184:187], v188 offset0:224 offset1:228
	s_waitcnt lgkmcnt(0)
	v_mfma_f32_16x16x32_bf16 v[92:95], v[184:187], v[92:95], 0
	ds_read2_b64 v[184:187], v189 offset0:224 offset1:228
	s_waitcnt lgkmcnt(0)
	v_mfma_f32_16x16x32_bf16 v[92:95], v[184:187], v[100:103], v[92:95]
	ds_read2_b64 v[184:187], v188 offset0:232 offset1:236
	s_waitcnt lgkmcnt(0)
	v_mfma_f32_16x16x32_bf16 v[36:39], v[184:187], v[36:39], v[92:95]
	s_nop 4
	ds_read2_b64 v[92:95], v189 offset0:232 offset1:236
	s_waitcnt lgkmcnt(0)
	v_mfma_f32_16x16x32_bf16 v[36:39], v[92:95], v[96:99], v[36:39]
	v_mov_b32_e32 v92, s58
	ds_read_b32 v184, v92 offset:63488
	s_lshl_b32 s58, s71, 10
	s_waitcnt lgkmcnt(0)
	v_mul_f32_e32 v2, v184, v2
	v_mul_f32_e32 v3, v184, v3
	v_mul_f32_e32 v0, v184, v0
	v_mul_f32_e32 v1, v184, v1
	v_add_u32_e32 v185, 0x4800, v179
	ds_read2_b64 v[92:95], v185 offset1:4
	s_waitcnt lgkmcnt(0)
	v_mfma_f32_16x16x32_bf16 v[0:3], v[92:95], v[100:103], v[0:3]
	ds_read2_b64 v[92:95], v185 offset0:8 offset1:12
	v_mul_f32_e32 v6, v184, v6
	v_mul_f32_e32 v7, v184, v7
	v_mul_f32_e32 v4, v184, v4
	v_mul_f32_e32 v5, v184, v5
	v_add_u32_e32 v185, 0x5000, v179
	s_waitcnt lgkmcnt(0)
	v_mfma_f32_16x16x32_bf16 v[0:3], v[92:95], v[96:99], v[0:3]
	ds_read2_b64 v[92:95], v185 offset0:32 offset1:36
	v_mul_f32_e32 v10, v184, v10
	v_mul_f32_e32 v11, v184, v11
	v_mul_f32_e32 v8, v184, v8
	v_mul_f32_e32 v9, v184, v9
	s_waitcnt lgkmcnt(0)
	v_mfma_f32_16x16x32_bf16 v[4:7], v[92:95], v[100:103], v[4:7]
	ds_read2_b64 v[92:95], v185 offset0:40 offset1:44
	v_add_u32_e32 v185, 0x5800, v179
	v_add_u32_e32 v179, 0x6000, v179
	s_waitcnt lgkmcnt(0)
	v_mfma_f32_16x16x32_bf16 v[4:7], v[92:95], v[96:99], v[4:7]
	ds_read2_b64 v[92:95], v185 offset0:64 offset1:68
	v_mul_f32_e32 v14, v184, v14
	v_mul_f32_e32 v15, v184, v15
	v_mul_f32_e32 v12, v184, v12
	v_mul_f32_e32 v13, v184, v13
	s_waitcnt lgkmcnt(0)
	v_mfma_f32_16x16x32_bf16 v[8:11], v[92:95], v[100:103], v[8:11]
	ds_read2_b64 v[92:95], v185 offset0:72 offset1:76
	s_waitcnt lgkmcnt(0)
	v_mfma_f32_16x16x32_bf16 v[8:11], v[92:95], v[96:99], v[8:11]
	ds_read2_b64 v[92:95], v179 offset0:96 offset1:100
	s_waitcnt lgkmcnt(0)
	v_mfma_f32_16x16x32_bf16 v[12:15], v[92:95], v[100:103], v[12:15]
	ds_read2_b64 v[92:95], v179 offset0:104 offset1:108
	s_waitcnt lgkmcnt(0)
	v_mfma_f32_16x16x32_bf16 v[12:15], v[92:95], v[96:99], v[12:15]
	v_mul_f32_e32 v92, v16, v16
	v_mov_b32_e32 v93, v25
	v_mov_b32_e32 v94, 0
	s_nop 0
	v_mov_b32_dpp v93, v92 quad_perm:[1,0,3,2] row_mask:0xf bank_mask:0xf
	v_fmac_f32_e32 v93, v16, v16
	s_nop 1
	v_add_f32_dpp v92, v93, v93 quad_perm:[2,3,0,1] row_mask:0xf bank_mask:0xf bound_ctrl:1
	s_nop 1
	v_add_f32_dpp v93, v92, v92 row_half_mirror row_mask:0xf bank_mask:0xf bound_ctrl:1
	v_add_u32_e32 v92, s58, v127
	s_nop 0
	v_mov_b32_dpp v94, v93 row_mirror row_mask:0xf bank_mask:0xf
	s_and_saveexec_b64 s[58:59], s[20:21]
	v_add_f32_e32 v93, v93, v94
	ds_write_b32 v92, v93
	s_or_b64 exec, exec, s[58:59]
	v_mul_f32_e32 v93, v17, v17
	v_mov_b32_e32 v94, v25
	s_nop 1
	v_mov_b32_dpp v94, v93 quad_perm:[1,0,3,2] row_mask:0xf bank_mask:0xf
	v_fmac_f32_e32 v94, v17, v17
	s_nop 1
	v_add_f32_dpp v93, v94, v94 quad_perm:[2,3,0,1] row_mask:0xf bank_mask:0xf bound_ctrl:1
	v_mov_b32_e32 v94, 0
	s_nop 0
	v_add_f32_dpp v93, v93, v93 row_half_mirror row_mask:0xf bank_mask:0xf bound_ctrl:1
	s_nop 1
	v_mov_b32_dpp v94, v93 row_mirror row_mask:0xf bank_mask:0xf
	s_and_saveexec_b64 s[58:59], s[20:21]
	v_add_f32_e32 v93, v93, v94
	ds_write_b32 v92, v93 offset:4
	s_or_b64 exec, exec, s[58:59]
	v_mul_f32_e32 v93, v18, v18
	v_mov_b32_e32 v94, v25
	s_nop 1
	v_mov_b32_dpp v94, v93 quad_perm:[1,0,3,2] row_mask:0xf bank_mask:0xf
	v_fmac_f32_e32 v94, v18, v18
	s_nop 1
	v_add_f32_dpp v93, v94, v94 quad_perm:[2,3,0,1] row_mask:0xf bank_mask:0xf bound_ctrl:1
	v_mov_b32_e32 v94, 0
	s_nop 0
	v_add_f32_dpp v93, v93, v93 row_half_mirror row_mask:0xf bank_mask:0xf bound_ctrl:1
	s_nop 1
	v_mov_b32_dpp v94, v93 row_mirror row_mask:0xf bank_mask:0xf
	s_and_saveexec_b64 s[58:59], s[20:21]
	v_add_f32_e32 v93, v93, v94
	ds_write_b32 v92, v93 offset:8
	s_or_b64 exec, exec, s[58:59]
	v_mul_f32_e32 v93, v19, v19
	v_mov_b32_e32 v94, v25
	s_nop 1
	v_mov_b32_dpp v94, v93 quad_perm:[1,0,3,2] row_mask:0xf bank_mask:0xf
	v_fmac_f32_e32 v94, v19, v19
	s_nop 1
	v_add_f32_dpp v93, v94, v94 quad_perm:[2,3,0,1] row_mask:0xf bank_mask:0xf bound_ctrl:1
	v_mov_b32_e32 v94, 0
	s_nop 0
	v_add_f32_dpp v93, v93, v93 row_half_mirror row_mask:0xf bank_mask:0xf bound_ctrl:1
	s_nop 1
	v_mov_b32_dpp v94, v93 row_mirror row_mask:0xf bank_mask:0xf
	s_and_saveexec_b64 s[58:59], s[20:21]
	v_add_f32_e32 v93, v93, v94
	ds_write_b32 v92, v93 offset:12
	s_or_b64 exec, exec, s[58:59]
	v_mul_f32_e32 v93, v20, v20
	v_mov_b32_e32 v94, v25
	s_nop 1
	v_mov_b32_dpp v94, v93 quad_perm:[1,0,3,2] row_mask:0xf bank_mask:0xf
	v_fmac_f32_e32 v94, v20, v20
	s_nop 1
	v_add_f32_dpp v93, v94, v94 quad_perm:[2,3,0,1] row_mask:0xf bank_mask:0xf bound_ctrl:1
	v_mov_b32_e32 v94, 0
	s_nop 0
	v_add_f32_dpp v93, v93, v93 row_half_mirror row_mask:0xf bank_mask:0xf bound_ctrl:1
	s_nop 1
	v_mov_b32_dpp v94, v93 row_mirror row_mask:0xf bank_mask:0xf
	s_and_saveexec_b64 s[58:59], s[20:21]
	v_add_f32_e32 v93, v93, v94
	ds_write_b32 v92, v93 offset:64
	s_or_b64 exec, exec, s[58:59]
	v_mul_f32_e32 v93, v21, v21
	v_mov_b32_e32 v94, v25
	s_nop 1
	v_mov_b32_dpp v94, v93 quad_perm:[1,0,3,2] row_mask:0xf bank_mask:0xf
; #define LAS __attribute__((address_space(3)))
; __device__ __forceinline__ float row16_sum(float v) { v += dpp_f<0xB1>(v); v += dpp_f<0x4E>(v); v += dpp_f<0x141>(v); v += dpp_f<0x140>(v); return v; }
; __device__ __forceinline__ void g2_phase(const PP P, int l, LAS unsigned char* lds) {
;     ...
;                     for (int j = 0; j < 4; ++j) { const int i = 16 * mi + fq * 4 + j; U[mi][j] = *(const LAS float*)(buf + G2_UV + i * 272 + dv * 4) - acc[j];
;                         zr[mi][j] = bf2f(*(const LAS bf16*)(buf + G2_Z + i * 144 + dv * 2)); } }
;     ...
; #pragma unroll
;                 for (int mi = 0; mi < 4; ++mi)
; #pragma unroll
;                     for (int j = 0; j < 4; ++j) { const float s = row16_sum(O[mi][j] * O[mi][j]);
;                         if (fr == 0) red[(n & 1) * 256 + wave * 64 + 16 * mi + fq * 4 + j] = s; }
	v_fmac_f32_e32 v94, v21, v21
	s_nop 1
	v_add_f32_dpp v93, v94, v94 quad_perm:[2,3,0,1] row_mask:0xf bank_mask:0xf bound_ctrl:1
	v_mov_b32_e32 v94, 0
	s_nop 0
	v_add_f32_dpp v93, v93, v93 row_half_mirror row_mask:0xf bank_mask:0xf bound_ctrl:1
	s_nop 1
	v_mov_b32_dpp v94, v93 row_mirror row_mask:0xf bank_mask:0xf
	s_and_saveexec_b64 s[58:59], s[20:21]
	v_add_f32_e32 v93, v93, v94
	ds_write_b32 v92, v93 offset:68
	s_or_b64 exec, exec, s[58:59]
	v_mul_f32_e32 v93, v22, v22
	v_mov_b32_e32 v94, v25
	s_nop 1
	v_mov_b32_dpp v94, v93 quad_perm:[1,0,3,2] row_mask:0xf bank_mask:0xf
	v_fmac_f32_e32 v94, v22, v22
	s_nop 1
	v_add_f32_dpp v93, v94, v94 quad_perm:[2,3,0,1] row_mask:0xf bank_mask:0xf bound_ctrl:1
	v_mov_b32_e32 v94, 0
	s_nop 0
	v_add_f32_dpp v93, v93, v93 row_half_mirror row_mask:0xf bank_mask:0xf bound_ctrl:1
	s_nop 1
	v_mov_b32_dpp v94, v93 row_mirror row_mask:0xf bank_mask:0xf
	s_and_saveexec_b64 s[58:59], s[20:21]
	v_add_f32_e32 v93, v93, v94
	ds_write_b32 v92, v93 offset:72
	s_or_b64 exec, exec, s[58:59]
	v_mul_f32_e32 v93, v23, v23
	v_mov_b32_e32 v94, v25
	s_nop 1
	v_mov_b32_dpp v94, v93 quad_perm:[1,0,3,2] row_mask:0xf bank_mask:0xf
	v_fmac_f32_e32 v94, v23, v23
	s_nop 1
	v_add_f32_dpp v93, v94, v94 quad_perm:[2,3,0,1] row_mask:0xf bank_mask:0xf bound_ctrl:1
	v_mov_b32_e32 v94, 0
	s_nop 0
	v_add_f32_dpp v93, v93, v93 row_half_mirror row_mask:0xf bank_mask:0xf bound_ctrl:1
	s_nop 1
	v_mov_b32_dpp v94, v93 row_mirror row_mask:0xf bank_mask:0xf
	s_and_saveexec_b64 s[58:59], s[20:21]
	v_add_f32_e32 v93, v93, v94
	ds_write_b32 v92, v93 offset:76
	s_or_b64 exec, exec, s[58:59]
	v_mul_f32_e32 v93, v28, v28
	v_mov_b32_e32 v94, v25
	s_nop 1
	v_mov_b32_dpp v94, v93 quad_perm:[1,0,3,2] row_mask:0xf bank_mask:0xf
	v_fmac_f32_e32 v94, v28, v28
	s_nop 1
	v_add_f32_dpp v93, v94, v94 quad_perm:[2,3,0,1] row_mask:0xf bank_mask:0xf bound_ctrl:1
	v_mov_b32_e32 v94, 0
	s_nop 0
	v_add_f32_dpp v93, v93, v93 row_half_mirror row_mask:0xf bank_mask:0xf bound_ctrl:1
	s_nop 1
	v_mov_b32_dpp v94, v93 row_mirror row_mask:0xf bank_mask:0xf
	s_and_saveexec_b64 s[58:59], s[20:21]
	v_add_f32_e32 v93, v93, v94
	ds_write_b32 v92, v93 offset:128
	s_or_b64 exec, exec, s[58:59]
	v_mul_f32_e32 v93, v29, v29
	v_mov_b32_e32 v94, v25
	s_nop 1
	v_mov_b32_dpp v94, v93 quad_perm:[1,0,3,2] row_mask:0xf bank_mask:0xf
	v_fmac_f32_e32 v94, v29, v29
	s_nop 1
	v_add_f32_dpp v93, v94, v94 quad_perm:[2,3,0,1] row_mask:0xf bank_mask:0xf bound_ctrl:1
	v_mov_b32_e32 v94, 0
	s_nop 0
	v_add_f32_dpp v93, v93, v93 row_half_mirror row_mask:0xf bank_mask:0xf bound_ctrl:1
	s_nop 1
	v_mov_b32_dpp v94, v93 row_mirror row_mask:0xf bank_mask:0xf
	s_and_saveexec_b64 s[58:59], s[20:21]
	v_add_f32_e32 v93, v93, v94
	ds_write_b32 v92, v93 offset:132
	s_or_b64 exec, exec, s[58:59]
	v_mul_f32_e32 v93, v30, v30
	v_mov_b32_e32 v94, v25
	s_nop 1
	v_mov_b32_dpp v94, v93 quad_perm:[1,0,3,2] row_mask:0xf bank_mask:0xf
	v_fmac_f32_e32 v94, v30, v30
	s_nop 1
	v_add_f32_dpp v93, v94, v94 quad_perm:[2,3,0,1] row_mask:0xf bank_mask:0xf bound_ctrl:1
	v_mov_b32_e32 v94, 0
	s_nop 0
	v_add_f32_dpp v93, v93, v93 row_half_mirror row_mask:0xf bank_mask:0xf bound_ctrl:1
	s_nop 1
	v_mov_b32_dpp v94, v93 row_mirror row_mask:0xf bank_mask:0xf
	s_and_saveexec_b64 s[58:59], s[20:21]
	v_add_f32_e32 v93, v93, v94
	ds_write_b32 v92, v93 offset:136
	s_or_b64 exec, exec, s[58:59]
	v_mul_f32_e32 v93, v31, v31
	v_mov_b32_e32 v94, v25
	s_nop 1
	v_mov_b32_dpp v94, v93 quad_perm:[1,0,3,2] row_mask:0xf bank_mask:0xf
	v_fmac_f32_e32 v94, v31, v31
	s_nop 1
	v_add_f32_dpp v93, v94, v94 quad_perm:[2,3,0,1] row_mask:0xf bank_mask:0xf bound_ctrl:1
	v_mov_b32_e32 v94, 0
	s_nop 0
	v_add_f32_dpp v93, v93, v93 row_half_mirror row_mask:0xf bank_mask:0xf bound_ctrl:1
	s_nop 1
	v_mov_b32_dpp v94, v93 row_mirror row_mask:0xf bank_mask:0xf
	s_and_saveexec_b64 s[58:59], s[20:21]
	v_add_f32_e32 v93, v93, v94
	ds_write_b32 v92, v93 offset:140
	s_or_b64 exec, exec, s[58:59]
	v_mul_f32_e32 v93, v36, v36
	v_mov_b32_e32 v94, v25
	s_nop 1
	v_mov_b32_dpp v94, v93 quad_perm:[1,0,3,2] row_mask:0xf bank_mask:0xf
	v_fmac_f32_e32 v94, v36, v36
	s_nop 1
	v_add_f32_dpp v93, v94, v94 quad_perm:[2,3,0,1] row_mask:0xf bank_mask:0xf bound_ctrl:1
	v_mov_b32_e32 v94, 0
	s_nop 0
	v_add_f32_dpp v93, v93, v93 row_half_mirror row_mask:0xf bank_mask:0xf bound_ctrl:1
	s_nop 1
	v_mov_b32_dpp v94, v93 row_mirror row_mask:0xf bank_mask:0xf
	s_and_saveexec_b64 s[58:59], s[20:21]
	v_add_f32_e32 v93, v93, v94
	ds_write_b32 v92, v93 offset:192
	s_or_b64 exec, exec, s[58:59]
	v_mul_f32_e32 v93, v37, v37
	v_mov_b32_e32 v94, v25
	s_nop 1
	v_mov_b32_dpp v94, v93 quad_perm:[1,0,3,2] row_mask:0xf bank_mask:0xf
	v_fmac_f32_e32 v94, v37, v37
	s_nop 1
	v_add_f32_dpp v93, v94, v94 quad_perm:[2,3,0,1] row_mask:0xf bank_mask:0xf bound_ctrl:1
	v_mov_b32_e32 v94, 0
	s_nop 0
	v_add_f32_dpp v93, v93, v93 row_half_mirror row_mask:0xf bank_mask:0xf bound_ctrl:1
	s_nop 1
	v_mov_b32_dpp v94, v93 row_mirror row_mask:0xf bank_mask:0xf
	s_and_saveexec_b64 s[58:59], s[20:21]
	v_add_f32_e32 v93, v93, v94
	ds_write_b32 v92, v93 offset:196
	s_or_b64 exec, exec, s[58:59]
	v_mul_f32_e32 v93, v38, v38
	v_mov_b32_e32 v94, v25
	s_nop 1
	v_mov_b32_dpp v94, v93 quad_perm:[1,0,3,2] row_mask:0xf bank_mask:0xf
	v_fmac_f32_e32 v94, v38, v38
	s_nop 1
	v_add_f32_dpp v93, v94, v94 quad_perm:[2,3,0,1] row_mask:0xf bank_mask:0xf bound_ctrl:1
	v_mov_b32_e32 v94, 0
	s_nop 0
	v_add_f32_dpp v93, v93, v93 row_half_mirror row_mask:0xf bank_mask:0xf bound_ctrl:1
	s_nop 1
	v_mov_b32_dpp v94, v93 row_mirror row_mask:0xf bank_mask:0xf
	s_and_saveexec_b64 s[58:59], s[20:21]
	v_add_f32_e32 v93, v93, v94
	ds_write_b32 v92, v93 offset:200
	s_or_b64 exec, exec, s[58:59]
	v_mul_f32_e32 v93, v39, v39
	v_mov_b32_e32 v94, v25
	s_nop 1
	v_mov_b32_dpp v94, v93 quad_perm:[1,0,3,2] row_mask:0xf bank_mask:0xf
	v_fmac_f32_e32 v94, v39, v39
	s_nop 1
	v_add_f32_dpp v93, v94, v94 quad_perm:[2,3,0,1] row_mask:0xf bank_mask:0xf bound_ctrl:1
	v_mov_b32_e32 v94, 0
	s_nop 0
	v_add_f32_dpp v93, v93, v93 row_half_mirror row_mask:0xf bank_mask:0xf bound_ctrl:1
	s_nop 1
	v_mov_b32_dpp v94, v93 row_mirror row_mask:0xf bank_mask:0xf
	s_and_saveexec_b64 s[58:59], s[20:21]
	v_add_f32_e32 v93, v93, v94
	ds_write_b32 v92, v93 offset:204
	s_or_b64 exec, exec, s[58:59]
	v_lshlrev_b32_e32 v93, 16, v24
	v_lshlrev_b32_e32 v92, 16, v154
	v_lshlrev_b32_e32 v95, 16, v148
	v_lshlrev_b32_e32 v94, 16, v155
	v_lshlrev_b32_e32 v97, 16, v158
	v_lshlrev_b32_e32 v96, 16, v156
	v_lshlrev_b32_e32 v99, 16, v159
	v_lshlrev_b32_e32 v98, 16, v157
	v_lshlrev_b32_e32 v101, 16, v163
	v_lshlrev_b32_e32 v100, 16, v161
	v_lshlrev_b32_e32 v103, 16, v178
	v_lshlrev_b32_e32 v102, 16, v162
	v_lshlrev_b32_e32 v155, 16, v182
	v_lshlrev_b32_e32 v154, 16, v180
	v_lshlrev_b32_e32 v157, 16, v183
	v_lshlrev_b32_e32 v156, 16, v181
